# P0 weight tiles on waves 0..3 of every workgroup (one per SIMD) instead of the even waves
# baseline (speedup 1.0000x reference)
.LBB0_24:
	v_writelane_b32 v253, s36, 42
	s_nop 1
	v_writelane_b32 v253, s37, 43
	v_writelane_b32 v253, s34, 44
	s_nop 1
	v_writelane_b32 v253, s35, 45
	s_or_b64 exec, exec, s[4:5]
	s_load_dwordx16 s[12:27], s[0:1], 0x0
	s_lshl_b32 s38, s78, 3
	s_waitcnt lgkmcnt(0)
	v_writelane_b32 v253, s12, 26
	s_nop 1
	v_writelane_b32 v253, s13, 27
	v_writelane_b32 v253, s14, 28
	v_writelane_b32 v253, s15, 29
	v_writelane_b32 v253, s16, 30
	v_writelane_b32 v253, s17, 31
	v_writelane_b32 v253, s18, 32
	v_writelane_b32 v253, s19, 33
	v_writelane_b32 v253, s20, 34
	v_writelane_b32 v253, s21, 35
	v_writelane_b32 v253, s22, 36
	v_writelane_b32 v253, s23, 37
	v_writelane_b32 v253, s24, 38
	v_writelane_b32 v253, s25, 39
	v_writelane_b32 v253, s26, 40
	v_writelane_b32 v253, s27, 41
	s_load_dwordx16 s[12:27], s[0:1], 0x40
	s_lshr_b32 s0, s8, 6
	s_lshl_b32 s1, s2, 3
	s_add_i32 s36, s0, s1
	s_waitcnt lgkmcnt(0)
	v_writelane_b32 v253, s12, 10
	s_nop 1
	v_writelane_b32 v253, s13, 11
	v_writelane_b32 v253, s14, 12
	v_writelane_b32 v253, s15, 13
	v_writelane_b32 v253, s16, 14
	v_writelane_b32 v253, s17, 15
	v_writelane_b32 v253, s18, 16
	v_writelane_b32 v253, s19, 17
	v_writelane_b32 v253, s20, 18
	v_writelane_b32 v253, s21, 19
	v_writelane_b32 v253, s22, 20
	v_writelane_b32 v253, s23, 21
	v_writelane_b32 v253, s24, 22
	v_writelane_b32 v253, s25, 23
	v_writelane_b32 v253, s26, 24
	v_writelane_b32 v253, s27, 25
	s_nop 0
	v_readlane_b32 s8, v253, 0
	v_readlane_b32 s10, v253, 2
	v_readlane_b32 s11, v253, 3
	s_add_u32 s64, s10, 0x400000
	s_addc_u32 s65, s11, 0
	s_cmpk_gt_i32 s36, 0x2fff
	v_readlane_b32 s9, v253, 1
	s_cbranch_scc1 .LBB0_178
	v_and_b32_e32 v219, 31, v227
	v_lshlrev_b32_e32 v212, 4, v219
	v_lshrrev_b32_e32 v213, 5, v227
	v_lshlrev_b32_e32 v214, 2, v219
	v_and_b32_e32 v215, 64, v214
	v_add_u32_e32 v215, v215, v214
	v_lshlrev_b32_e32 v216, 5, v213
	v_readlane_b32 s8, v253, 36
	v_readlane_b32 s9, v253, 37
	v_readlane_b32 s10, v253, 34
	v_readlane_b32 s11, v253, 35
	v_readlane_b32 s12, v253, 16
	v_readlane_b32 s13, v253, 17
	v_readlane_b32 s14, v253, 18
	v_readlane_b32 s15, v253, 19
	v_readlane_b32 s16, v253, 20
	v_readlane_b32 s17, v253, 21
	v_readlane_b32 s18, v253, 22
	v_readlane_b32 s19, v253, 23
	s_mov_b32 s66, s36
	s_movk_i32 s98, 0x17ff
	s_mov_b32 s99, s38
	s_cmpk_eq_u32 s78, 0x100
	s_cbranch_scc0 .Lwt_loop
	s_movk_i32 s98, 0x3ff
	s_movk_i32 s99, 0x400
	s_and_b32 s66, s36, 7
	s_cmpk_lt_u32 s66, 4
	s_cselect_b32 s67, 0, 0x7fff
	s_lshr_b32 s100, s36, 3
	s_lshl_b32 s100, s100, 2
	s_add_i32 s66, s66, s100
	s_or_b32 s66, s66, s67
